# layer-prep pool-weight folding: the 8 sequential dot-product loops fused into one loop with batched loads
# speedup vs baseline: 1.0014x; 1.0014x over previous
; __device__ __forceinline__ unsigned cvt_pk_bf16(float lo, float hi) { const f32x2_ v = {lo, hi}; return __builtin_bit_cast(unsigned, __builtin_convertvector(v, bf16x2_)); }
; __device__ __forceinline__ int opaque_tid() { int t = threadIdx.x; asm volatile("" : "+v"(t)); return t; }
; template <class F>
; __device__ __forceinline__ void wt_rows64(bf16_t* dst, int K, F srcval, int ldd, int kbeg, int kend) {
;     if (ldd == 0) ldd = K;
;     if (kend > K) kend = K;
;     const int tid_ = opaque_tid(); const int nl = tid_ & 63, kq = tid_ >> 6;
;     for (int k0 = kbeg + kq * 8; k0 < kend; k0 += 64) {
;         float v[8];
; #pragma unroll
;         for (int j = 0; j < 8; ++j) v[j] = srcval(nl, k0 + j);
;         u32x4 w; w.x = cvt_pk_bf16(v[0], v[1]); w.y = cvt_pk_bf16(v[2], v[3]); w.z = cvt_pk_bf16(v[4], v[5]); w.w = cvt_pk_bf16(v[6], v[7]);
;         *(u32x4*)(dst + (size_t)nl * ldd + k0) = w;
; __device__ void layer_prep_phase(PK p, int l, LAS unsigned char* lds) {
;     ...
;         } else if (it < 388) {
;             const int j = it - 372; const float* wb = p->branch_w_out + ((size_t)(l * 4) * 256) * 1024; const float* pw = p->pool_w + (size_t)l * 4 * 64 * 64; const float* ps = p->pool_scale + l * 256;
;             bf16_t* dst = (bf16_t*)(ws + OFF_WB) + (size_t)j * 64 * 1024;
;             wt_rows64(dst, 256, [&](int nl, int k) { const int gI = k >> 6, n = j * 64 + nl; const float* pr = pw + (size_t)k * 64; float s = 0.f;
;                 for (int e = 0; e < 64; ++e) s += pr[e] * ps[gI * 64 + e] * wb[(size_t)(gI * 64 + e) * 1024 + n]; return s; }, 1024, kbeg, kend);
.LBB0_783:
	v_and_b32_e32 v28, 0xffffffc0, v2
	v_ashrrev_i32_e32 v29, 31, v28
	v_lshlrev_b64 v[26:27], 12, v[28:29]
	v_lshl_add_u64 v[26:27], v[6:7], 0, v[26:27]
	v_lshl_add_u64 v[28:29], v[28:29], 2, s[6:7]
	v_mov_b32_e32 v1, 0
	v_mov_b32_e32 v11, 0
	v_mov_b32_e32 v15, 0
	v_mov_b32_e32 v17, 0
	v_mov_b32_e32 v19, 0
	v_mov_b32_e32 v21, 0
	v_mov_b32_e32 v23, 0
	v_mov_b32_e32 v25, 0
	s_mov_b64 s[0:1], 0
	s_mov_b64 s[10:11], 0
; __device__ __forceinline__ unsigned cvt_pk_bf16(float lo, float hi) { const f32x2_ v = {lo, hi}; return __builtin_bit_cast(unsigned, __builtin_convertvector(v, bf16x2_)); }
; template <class F>
; __device__ __forceinline__ void wt_rows64(bf16_t* dst, int K, F srcval, int ldd, int kbeg, int kend) {
;     ...
;     for (int k0 = kbeg + kq * 8; k0 < kend; k0 += 64) {
;         float v[8];
; #pragma unroll
;         for (int j = 0; j < 8; ++j) v[j] = srcval(nl, k0 + j);
;         u32x4 w; w.x = cvt_pk_bf16(v[0], v[1]); w.y = cvt_pk_bf16(v[2], v[3]); w.z = cvt_pk_bf16(v[4], v[5]); w.w = cvt_pk_bf16(v[6], v[7]);
;         *(u32x4*)(dst + (size_t)nl * ldd + k0) = w;
; __device__ void layer_prep_phase(PK p, int l, LAS unsigned char* lds) {
;     ...
;             const int j = it - 372; const float* wb = p->branch_w_out + ((size_t)(l * 4) * 256) * 1024; const float* pw = p->pool_w + (size_t)l * 4 * 64 * 64; const float* ps = p->pool_scale + l * 256;
;             bf16_t* dst = (bf16_t*)(ws + OFF_WB) + (size_t)j * 64 * 1024;
;             wt_rows64(dst, 256, [&](int nl, int k) { const int gI = k >> 6, n = j * 64 + nl; const float* pr = pw + (size_t)k * 64; float s = 0.f;
;                 for (int e = 0; e < 64; ++e) s += pr[e] * ps[gI * 64 + e] * wb[(size_t)(gI * 64 + e) * 1024 + n]; return s; }, 1024, kbeg, kend);
.Lwb0_loop:
	v_lshl_add_u64 v[140:141], v[28:29], 0, s[0:1]
	v_lshl_add_u64 v[46:47], v[26:27], 0, s[10:11]
	v_lshl_add_u64 v[142:143], v[8:9], 0, s[0:1]
	global_load_dwordx4 v[60:63], v[140:141], off
	global_load_dwordx4 v[64:67], v[140:141], off offset:16
	global_load_dword v68, v[46:47], off
	v_add_co_u32_e32 v48, vcc, s54, v46
	s_nop 1
	v_addc_co_u32_e32 v49, vcc, 0, v47, vcc
	v_add_co_u32_e32 v50, vcc, s55, v46
	s_nop 1
	v_addc_co_u32_e32 v51, vcc, 0, v47, vcc
	v_add_co_u32_e32 v52, vcc, s52, v46
	s_nop 1
	v_addc_co_u32_e32 v53, vcc, 0, v47, vcc
	v_add_co_u32_e32 v54, vcc, s92, v46
	s_nop 1
	v_addc_co_u32_e32 v55, vcc, 0, v47, vcc
	global_load_dword v69, v[48:49], off offset:-4096
	global_load_dword v70, v[48:49], off
	global_load_dword v71, v[50:51], off offset:-4096
	global_load_dword v72, v[50:51], off
	global_load_dword v73, v[52:53], off offset:-4096
	global_load_dword v74, v[52:53], off
	global_load_dword v75, v[54:55], off
	global_load_dwordx4 v[76:79], v[142:143], off
	global_load_dwordx4 v[80:83], v[142:143], off offset:16
	global_load_dwordx4 v[84:87], v[142:143], off offset:256
	global_load_dwordx4 v[88:91], v[142:143], off offset:272
	global_load_dwordx4 v[92:95], v[142:143], off offset:512
	global_load_dwordx4 v[96:99], v[142:143], off offset:528
	global_load_dwordx4 v[100:103], v[142:143], off offset:768
	global_load_dwordx4 v[104:107], v[142:143], off offset:784
	global_load_dwordx4 v[108:111], v[142:143], off offset:1024
	global_load_dwordx4 v[112:115], v[142:143], off offset:1040
	global_load_dwordx4 v[116:119], v[142:143], off offset:1280
	global_load_dwordx4 v[120:123], v[142:143], off offset:1296
	global_load_dwordx4 v[124:127], v[142:143], off offset:1536
	global_load_dwordx4 v[128:131], v[142:143], off offset:1552
	global_load_dwordx4 v[132:135], v[142:143], off offset:1792
	global_load_dwordx4 v[136:139], v[142:143], off offset:1808
	s_add_u32 s10, s10, 0x8000
	s_addc_u32 s11, s11, 0
	s_add_u32 s0, s0, 32
	s_addc_u32 s1, s1, 0
	s_waitcnt vmcnt(14)
	v_mul_f32_e32 v76, v76, v60
	v_mul_f32_e32 v77, v77, v61
	v_mul_f32_e32 v78, v78, v62
	v_mul_f32_e32 v79, v79, v63
	v_mul_f32_e32 v80, v80, v64
	v_mul_f32_e32 v81, v81, v65
	v_mul_f32_e32 v82, v82, v66
	v_mul_f32_e32 v83, v83, v67
	v_fmac_f32_e32 v1, v76, v68
	v_fmac_f32_e32 v1, v77, v69
	v_fmac_f32_e32 v1, v78, v70
	v_fmac_f32_e32 v1, v79, v71
	v_fmac_f32_e32 v1, v80, v72
	v_fmac_f32_e32 v1, v81, v73
	v_fmac_f32_e32 v1, v82, v74
	v_fmac_f32_e32 v1, v83, v75
	s_waitcnt vmcnt(12)
	v_mul_f32_e32 v84, v84, v60
	v_mul_f32_e32 v85, v85, v61
	v_mul_f32_e32 v86, v86, v62
	v_mul_f32_e32 v87, v87, v63
	v_mul_f32_e32 v88, v88, v64
	v_mul_f32_e32 v89, v89, v65
	v_mul_f32_e32 v90, v90, v66
	v_mul_f32_e32 v91, v91, v67
	v_fmac_f32_e32 v11, v84, v68
	v_fmac_f32_e32 v11, v85, v69
	v_fmac_f32_e32 v11, v86, v70
	v_fmac_f32_e32 v11, v87, v71
	v_fmac_f32_e32 v11, v88, v72
	v_fmac_f32_e32 v11, v89, v73
	v_fmac_f32_e32 v11, v90, v74
	v_fmac_f32_e32 v11, v91, v75
	s_waitcnt vmcnt(10)
	v_mul_f32_e32 v92, v92, v60
	v_mul_f32_e32 v93, v93, v61
	v_mul_f32_e32 v94, v94, v62
	v_mul_f32_e32 v95, v95, v63
	v_mul_f32_e32 v96, v96, v64
	v_mul_f32_e32 v97, v97, v65
	v_mul_f32_e32 v98, v98, v66
	v_mul_f32_e32 v99, v99, v67
	v_fmac_f32_e32 v15, v92, v68
	v_fmac_f32_e32 v15, v93, v69
	v_fmac_f32_e32 v15, v94, v70
	v_fmac_f32_e32 v15, v95, v71
	v_fmac_f32_e32 v15, v96, v72
	v_fmac_f32_e32 v15, v97, v73
	v_fmac_f32_e32 v15, v98, v74
	v_fmac_f32_e32 v15, v99, v75
	s_waitcnt vmcnt(8)
	v_mul_f32_e32 v100, v100, v60
	v_mul_f32_e32 v101, v101, v61
	v_mul_f32_e32 v102, v102, v62
	v_mul_f32_e32 v103, v103, v63
	v_mul_f32_e32 v104, v104, v64
	v_mul_f32_e32 v105, v105, v65
	v_mul_f32_e32 v106, v106, v66
	v_mul_f32_e32 v107, v107, v67
	v_fmac_f32_e32 v17, v100, v68
	v_fmac_f32_e32 v17, v101, v69
	v_fmac_f32_e32 v17, v102, v70
	v_fmac_f32_e32 v17, v103, v71
	v_fmac_f32_e32 v17, v104, v72
	v_fmac_f32_e32 v17, v105, v73
	v_fmac_f32_e32 v17, v106, v74
	v_fmac_f32_e32 v17, v107, v75
	s_waitcnt vmcnt(6)
	v_mul_f32_e32 v108, v108, v60
	v_mul_f32_e32 v109, v109, v61
	v_mul_f32_e32 v110, v110, v62
	v_mul_f32_e32 v111, v111, v63
	v_mul_f32_e32 v112, v112, v64
	v_mul_f32_e32 v113, v113, v65
	v_mul_f32_e32 v114, v114, v66
	v_mul_f32_e32 v115, v115, v67
	v_fmac_f32_e32 v19, v108, v68
	v_fmac_f32_e32 v19, v109, v69
	v_fmac_f32_e32 v19, v110, v70
	v_fmac_f32_e32 v19, v111, v71
	v_fmac_f32_e32 v19, v112, v72
	v_fmac_f32_e32 v19, v113, v73
	v_fmac_f32_e32 v19, v114, v74
	v_fmac_f32_e32 v19, v115, v75
	s_waitcnt vmcnt(4)
	v_mul_f32_e32 v116, v116, v60
	v_mul_f32_e32 v117, v117, v61
	v_mul_f32_e32 v118, v118, v62
	v_mul_f32_e32 v119, v119, v63
	v_mul_f32_e32 v120, v120, v64
	v_mul_f32_e32 v121, v121, v65
	v_mul_f32_e32 v122, v122, v66
	v_mul_f32_e32 v123, v123, v67
	v_fmac_f32_e32 v21, v116, v68
	v_fmac_f32_e32 v21, v117, v69
	v_fmac_f32_e32 v21, v118, v70
	v_fmac_f32_e32 v21, v119, v71
	v_fmac_f32_e32 v21, v120, v72
	v_fmac_f32_e32 v21, v121, v73
	v_fmac_f32_e32 v21, v122, v74
	v_fmac_f32_e32 v21, v123, v75
	s_waitcnt vmcnt(2)
	v_mul_f32_e32 v124, v124, v60
	v_mul_f32_e32 v125, v125, v61
	v_mul_f32_e32 v126, v126, v62
	v_mul_f32_e32 v127, v127, v63
	v_mul_f32_e32 v128, v128, v64
	v_mul_f32_e32 v129, v129, v65
	v_mul_f32_e32 v130, v130, v66
	v_mul_f32_e32 v131, v131, v67
	v_fmac_f32_e32 v23, v124, v68
	v_fmac_f32_e32 v23, v125, v69
	v_fmac_f32_e32 v23, v126, v70
	v_fmac_f32_e32 v23, v127, v71
	v_fmac_f32_e32 v23, v128, v72
	v_fmac_f32_e32 v23, v129, v73
	v_fmac_f32_e32 v23, v130, v74
	v_fmac_f32_e32 v23, v131, v75
	s_waitcnt vmcnt(0)
	v_mul_f32_e32 v132, v132, v60
	v_mul_f32_e32 v133, v133, v61
	v_mul_f32_e32 v134, v134, v62
	v_mul_f32_e32 v135, v135, v63
	v_mul_f32_e32 v136, v136, v64
	v_mul_f32_e32 v137, v137, v65
	v_mul_f32_e32 v138, v138, v66
	v_mul_f32_e32 v139, v139, v67
	v_fmac_f32_e32 v25, v132, v68
	v_fmac_f32_e32 v25, v133, v69
	v_fmac_f32_e32 v25, v134, v70
	v_fmac_f32_e32 v25, v135, v71
	v_fmac_f32_e32 v25, v136, v72
	v_fmac_f32_e32 v25, v137, v73
	v_fmac_f32_e32 v25, v138, v74
	v_fmac_f32_e32 v25, v139, v75
	s_cmp_lg_u32 s10, 0x40000
	s_cbranch_scc1 .Lwb0_loop
	v_ashrrev_i32_e32 v3, 31, v2
	v_lshl_add_u64 v[30:31], v[2:3], 1, v[4:5]
	v_add_u32_e32 v2, 64, v2
	s_mov_b64 s[0:1], 0x4000
	v_cmp_le_i32_e32 vcc, s38, v2
	v_cvt_pk_bf16_f32 v26, v1, v11
	v_cvt_pk_bf16_f32 v27, v15, v17
	v_cvt_pk_bf16_f32 v28, v19, v21
	v_cvt_pk_bf16_f32 v29, v23, v25
	v_lshl_add_u64 v[8:9], v[8:9], 0, s[0:1]
	v_add_u32_e32 v10, 64, v10
	v_add_u32_e32 v14, 64, v14
	v_add_u32_e32 v16, 64, v16
	v_add_u32_e32 v18, 64, v18
	v_add_u32_e32 v20, 64, v20
	v_add_u32_e32 v22, 64, v22
	s_or_b64 s[8:9], vcc, s[8:9]
	v_add_u32_e32 v24, 64, v24
	global_store_dwordx4 v[30:31], v[26:29], off
	s_andn2_b64 exec, exec, s[8:9]
	s_cbranch_execnz .LBB0_783
